# per-XCD barriers skip the L2 write-back (buffer_wbl2) when the XCD mapping is the physical one: producers/consumers of those barriers share one L2; on top of v67
# speedup vs baseline: 1.0162x; 1.0076x over previous
; __global__ void __launch_bounds__(512, 2) fwd_megakernel(Params p) {
;     ...
;   {
;     bool even = true;
;     for (int i = 0; i < 8; ++i) even = even && (__hip_atomic_load(ctl + i, __ATOMIC_RELAXED, __HIP_MEMORY_SCOPE_AGENT) == (gridDim.x >> 3));
;     if (!even || js >= (int)(gridDim.x >> 3)) { xs = blockIdx.x & 7; js = blockIdx.x >> 3; }
;   }
;   unsigned bar_target = 0;
;     ...
;   unsigned xbar_target = 0;
;     ...
;   const int jv = js * 2 + vhalf, nbv = (int)(gridDim.x >> 3) * 2;
.LBB0_367:
	s_add_u32 s24, s34, 0x34d0000
	s_addc_u32 s25, s35, 0
	s_add_u32 s26, s34, 0x38d0000
	s_addc_u32 s27, s35, 0
	s_add_u32 s48, s34, 0x3ed0000
	s_addc_u32 s49, s35, 0
	s_add_u32 s50, s34, 0x46d0000
	s_addc_u32 s51, s35, 0
	s_add_u32 s52, s34, 0x8ad0000
	s_addc_u32 s53, s35, 0
	s_add_u32 s4, s34, 0xced0000
	v_writelane_b32 v254, s60, 42
	s_addc_u32 s5, s35, 0
	v_writelane_b32 v254, s4, 43
	v_lshrrev_b32_e32 v0, 6, v211
	s_mov_b32 s92, 0x10000
	v_writelane_b32 v254, s5, 44
	s_add_u32 s4, s34, 0x12ed0000
	s_addc_u32 s5, s35, 0
	v_writelane_b32 v254, s4, 45
	s_movk_i32 s60, 0x104
	s_movk_i32 s73, 0x2c00
	v_writelane_b32 v254, s5, 46
	s_add_u32 s4, s34, 0x18ed0000
	s_addc_u32 s5, s35, 0
	v_writelane_b32 v254, s4, 47
	s_cmp_lt_i32 s64, s33
	s_movk_i32 s79, 0xffe0
	v_writelane_b32 v254, s5, 48
	s_cselect_b64 s[4:5], -1, 0
	s_and_b64 s[0:1], s[0:1], s[4:5]
	v_writelane_b32 v253, s0, 46
	s_and_b32 s4, s2, 7
	s_lshr_b32 s5, s2, 3
	s_and_b64 s[0:1], s[0:1], exec
	s_cselect_b32 s7, s64, s5
	s_cselect_b32 s0, s3, s4
	s_lshl_b32 s1, s7, 1
	v_readlane_b32 s6, v254, 12
	s_add_i32 s8, s1, s65
	s_lshr_b32 s1, s6, 2
	s_and_b32 s1, s1, 0x3ffffffe
	s_cmpk_lt_i32 s7, 0x160
	s_cselect_b64 s[4:5], -1, 0
	s_add_i32 s30, 0, 0x10000
	v_writelane_b32 v254, s1, 49
	s_movk_i32 s1, 0x500
	v_mov_b32_e32 v2, s30
	v_writelane_b32 v254, s4, 50
	v_mad_u32_u24 v217, v0, s1, v2
	s_ashr_i32 s1, s0, 31
	v_writelane_b32 v254, s5, 51
	s_lshl_b32 s28, s0, 4
	s_lshl_b64 s[4:5], s[0:1], 2
	s_add_u32 s1, s34, s4
	s_addc_u32 s3, s35, s5
	s_add_u32 s4, s1, 0x1cf100c0
	s_addc_u32 s5, s3, 0
	v_writelane_b32 v254, s4, 52
	s_cmp_lt_i32 s7, 64
	s_movk_i32 s1, 0x1100
	v_writelane_b32 v254, s5, 53
	s_cselect_b64 s[4:5], -1, 0
	s_cmp_lg_u64 s[34:35], 0
	s_cselect_b64 s[76:77], -1, 0
	s_add_u32 s14, s34, 0x1cf10080
	s_addc_u32 s15, s35, 0
	v_writelane_b32 v254, s4, 54
	s_cmpk_lt_i32 s7, 0x50
	v_mad_u32_u24 v218, v0, s1, v2
	v_writelane_b32 v254, s5, 55
	s_cselect_b64 s[4:5], -1, 0
	v_writelane_b32 v254, s4, 56
	s_cmpk_lt_i32 s7, 0x60
	s_mov_b32 s67, 0x3fffff0
	v_writelane_b32 v254, s5, 57
	v_writelane_b32 v254, s7, 58
	s_cselect_b64 s[4:5], -1, 0
	v_writelane_b32 v254, s4, 59
	s_add_u32 s1, s34, 0x8ad0600
	s_movk_i32 s88, 0x440
	v_writelane_b32 v254, s5, 60
	v_writelane_b32 v254, s1, 61
	s_addc_u32 s1, s35, 0
	s_cmpk_lt_i32 s8, 0x200
	s_cselect_b64 s[4:5], -1, 0
	v_writelane_b32 v253, s4, 0
	v_writelane_b32 v254, s1, 62
	s_lshl_b32 s1, s0, 5
	v_writelane_b32 v253, s5, 1
	v_writelane_b32 v253, s1, 2
	s_lshl_b32 s0, s0, 1
	v_writelane_b32 v253, s0, 3
	s_add_u32 s0, s34, 0x80
	v_writelane_b32 v253, s0, 4
	s_addc_u32 s0, s35, 0
	v_writelane_b32 v253, s0, 5
	s_add_u32 s0, s34, 0x46d0080
	v_writelane_b32 v253, s0, 6
	s_addc_u32 s0, s35, 0
	s_add_u32 s91, s34, 0x8ad0080
	s_addc_u32 s72, s35, 0
	v_writelane_b32 v253, s0, 7
	s_add_u32 s0, s34, 0xbb0080
	v_writelane_b32 v253, s0, 8
	s_addc_u32 s0, s35, 0
	v_writelane_b32 v253, s0, 9
	s_add_u32 s0, s34, 0x23e0080
	v_writelane_b32 v253, s0, 10
	s_addc_u32 s0, s35, 0
	v_writelane_b32 v253, s0, 11
	s_add_u32 s0, s34, 0x2930080
	v_writelane_b32 v253, s0, 12
	s_addc_u32 s0, s35, 0
	v_writelane_b32 v253, s0, 13
	s_add_u32 s0, s34, 0x3090080
	v_writelane_b32 v253, s0, 14
	s_addc_u32 s0, s35, 0
	v_writelane_b32 v253, s0, 15
	s_lshl_b32 s0, s2, 7
	s_lshl_b32 s1, s65, 6
	s_add_i32 s0, s0, s1
	v_writelane_b32 v253, s0, 16
	s_lshl_b32 s0, s6, 7
	v_writelane_b32 v253, s0, 17
	s_add_i32 s0, s66, 0
	s_add_i32 s1, s0, 32
	v_writelane_b32 v253, s1, 18
	s_add_i32 s1, s0, 48
	v_writelane_b32 v253, s1, 19
	s_add_i32 s0, s0, 56
	v_writelane_b32 v253, s0, 20
	s_add_u32 s0, s34, 0x22a0080
	v_writelane_b32 v253, s0, 21
	s_addc_u32 s0, s35, 0
	v_writelane_b32 v253, s0, 22
	s_add_u32 s0, s34, 0x1150080
	v_writelane_b32 v253, s0, 23
	s_addc_u32 s0, s35, 0
	v_writelane_b32 v253, s0, 24
	s_add_u32 s0, s34, 0x1d00080
	v_writelane_b32 v253, s0, 25
	s_addc_u32 s0, s35, 0
	v_writelane_b32 v253, s0, 26
	s_mov_b32 s1, 0
	v_writelane_b32 v253, s0, 27
	v_writelane_b32 v254, s8, 63
	s_movk_i32 s66, 0x880
	v_writelane_b32 v253, s1, 28
	s_mov_b32 s29, 0x800000
	v_mov_b32_e32 v210, 0x358637bd
	v_mbcnt_hi_u32_b32 v219, -1, v28
	v_mov_b32_e32 v220, 0xff800000
	v_mov_b32_e32 v221, 0x880
	s_mov_b32 s68, 0x70000
	s_movk_i32 s69, 0xb40
	s_movk_i32 s64, 0xc00
	s_movk_i32 s65, 0x180
	s_mov_b32 s74, 0
	s_mov_b32 s75, 0
	s_mov_b32 s86, 0x3a800000
	s_mov_b32 s94, 0x3aaaaaab
	s_mov_b64 s[82:83], 0x8000
	s_mov_b64 s[96:97], 0x4400
	s_mov_b32 s80, 0x3e800000
	v_writelane_b32 v253, s14, 29
	s_nop 1
	v_writelane_b32 v253, s15, 30
	s_branch .LBB0_371

; DI void grid_bar(unsigned* ctr, unsigned target) {
;   asm volatile("s_waitcnt vmcnt(0)" ::: "memory");
;   __syncthreads();
;   if (threadIdx.x == 0) {
;     __builtin_amdgcn_fence(__ATOMIC_RELEASE, "agent");
;     asm volatile("s_waitcnt vmcnt(0)" ::: "memory");
;     (void)__hip_atomic_fetch_add(ctr, 1u, __ATOMIC_RELAXED, __HIP_MEMORY_SCOPE_AGENT);
;     while (__hip_atomic_load(ctr, __ATOMIC_RELAXED, __HIP_MEMORY_SCOPE_AGENT) < target) __builtin_amdgcn_s_sleep(1);
;     __builtin_amdgcn_fence(__ATOMIC_ACQUIRE, "agent");
.LBB0_468:
	s_waitcnt vmcnt(0)
	s_add_i32 s8, s75, s33
	s_barrier
	s_mov_b64 s[0:1], exec
	v_readlane_b32 s2, v254, 13
	v_readlane_b32 s3, v254, 14
	s_and_b64 s[2:3], s[0:1], s[2:3]
	s_mov_b64 exec, s[2:3]
	s_cbranch_execz .LBB0_474
	s_mov_b64 s[2:3], exec
	v_readlane_b32 s99, v253, 46
	s_cmp_lg_u32 s99, 0
	s_cbranch_scc1 .Lxnowb_0
	buffer_wbl2 sc1
.Lxnowb_0:
	s_waitcnt vmcnt(0)
	s_waitcnt vmcnt(0)
	v_mbcnt_lo_u32_b32 v0, s2, 0
	v_mbcnt_hi_u32_b32 v0, s3, v0
	v_cmp_eq_u32_e32 vcc, 0, v0
	s_and_saveexec_b64 s[6:7], vcc
	s_cbranch_execz .LBB0_471
	s_bcnt1_i32_b64 s2, s[2:3]
	v_mov_b32_e32 v0, s2
	v_readlane_b32 s2, v254, 52
	v_readlane_b32 s3, v254, 53
	s_nop 4
	global_atomic_add v1, v0, s[2:3]

; DI void grid_bar(unsigned* ctr, unsigned target) {
;   asm volatile("s_waitcnt vmcnt(0)" ::: "memory");
;   __syncthreads();
;   if (threadIdx.x == 0) {
;     __builtin_amdgcn_fence(__ATOMIC_RELEASE, "agent");
;     asm volatile("s_waitcnt vmcnt(0)" ::: "memory");
;     (void)__hip_atomic_fetch_add(ctr, 1u, __ATOMIC_RELAXED, __HIP_MEMORY_SCOPE_AGENT);
;     while (__hip_atomic_load(ctr, __ATOMIC_RELAXED, __HIP_MEMORY_SCOPE_AGENT) < target) __builtin_amdgcn_s_sleep(1);
;     __builtin_amdgcn_fence(__ATOMIC_ACQUIRE, "agent");
.LBB0_1240:
	s_waitcnt vmcnt(0)
	v_readlane_b32 s0, v254, 12
	v_readlane_b32 s1, v253, 38
	s_mov_b32 s6, s1
	v_readlane_b32 s32, v253, 35
	v_readlane_b32 s14, v254, 52
	v_readlane_b32 s15, v254, 53
	s_add_i32 s32, s32, s33
	s_waitcnt lgkmcnt(0)
	s_barrier
	s_mov_b64 s[0:1], exec
	v_readlane_b32 s2, v254, 13
	v_readlane_b32 s3, v254, 14
	s_and_b64 s[2:3], s[0:1], s[2:3]
	s_movk_i32 s79, 0xffe0
	s_mov_b64 exec, s[2:3]
	s_cbranch_execz .LBB0_1246
	s_mov_b64 s[2:3], exec
	v_readlane_b32 s99, v253, 46
	s_cmp_lg_u32 s99, 0
	s_cbranch_scc1 .Lxnowb_2
	buffer_wbl2 sc1
.Lxnowb_2:
	s_waitcnt vmcnt(0)
	s_waitcnt vmcnt(0)
	v_mbcnt_lo_u32_b32 v0, s2, 0
	v_mbcnt_hi_u32_b32 v0, s3, v0
	v_cmp_eq_u32_e32 vcc, 0, v0
	s_and_saveexec_b64 s[8:9], vcc
	s_cbranch_execz .LBB0_1243
	s_bcnt1_i32_b64 s2, s[2:3]
	v_mov_b32_e32 v0, s2
	global_atomic_add v1, v0, s[14:15]

; DI void grid_bar(unsigned* ctr, unsigned target) {
;   asm volatile("s_waitcnt vmcnt(0)" ::: "memory");
;   __syncthreads();
;   if (threadIdx.x == 0) {
;     __builtin_amdgcn_fence(__ATOMIC_RELEASE, "agent");
;     asm volatile("s_waitcnt vmcnt(0)" ::: "memory");
;     (void)__hip_atomic_fetch_add(ctr, 1u, __ATOMIC_RELAXED, __HIP_MEMORY_SCOPE_AGENT);
;     while (__hip_atomic_load(ctr, __ATOMIC_RELAXED, __HIP_MEMORY_SCOPE_AGENT) < target) __builtin_amdgcn_s_sleep(1);
;     __builtin_amdgcn_fence(__ATOMIC_ACQUIRE, "agent");
.LBB0_1460:
	s_waitcnt vmcnt(0)
	v_readlane_b32 s0, v254, 12
	s_mov_b32 s74, s56
	v_readlane_b32 s32, v253, 35
	v_readlane_b32 s14, v254, 52
	v_readlane_b32 s15, v254, 53
	s_add_i32 s32, s32, s33
	s_barrier
	s_mov_b64 s[0:1], exec
	v_readlane_b32 s2, v254, 13
	v_readlane_b32 s3, v254, 14
	s_and_b64 s[2:3], s[0:1], s[2:3]
	s_mov_b64 exec, s[2:3]
	s_cbranch_execz .LBB0_1466
	s_mov_b64 s[2:3], exec
	v_readlane_b32 s99, v253, 46
	s_cmp_lg_u32 s99, 0
	s_cbranch_scc1 .Lxnowb_3
	buffer_wbl2 sc1

; DI void grid_bar(unsigned* ctr, unsigned target) {
;   asm volatile("s_waitcnt vmcnt(0)" ::: "memory");
;   __syncthreads();
;   if (threadIdx.x == 0) {
;     __builtin_amdgcn_fence(__ATOMIC_RELEASE, "agent");
;     asm volatile("s_waitcnt vmcnt(0)" ::: "memory");
;     (void)__hip_atomic_fetch_add(ctr, 1u, __ATOMIC_RELAXED, __HIP_MEMORY_SCOPE_AGENT);
;     while (__hip_atomic_load(ctr, __ATOMIC_RELAXED, __HIP_MEMORY_SCOPE_AGENT) < target) __builtin_amdgcn_s_sleep(1);
;     __builtin_amdgcn_fence(__ATOMIC_ACQUIRE, "agent");
.LBB0_1658:
	s_waitcnt vmcnt(0)
	v_readlane_b32 s0, v254, 12
	s_mov_b32 s74, s58
	v_readlane_b32 s32, v253, 35
	v_readlane_b32 s14, v254, 52
	v_readlane_b32 s15, v254, 53
	s_add_i32 s32, s32, s33
	s_barrier
	s_mov_b64 s[0:1], exec
	v_readlane_b32 s2, v254, 13
	v_readlane_b32 s3, v254, 14
	s_and_b64 s[2:3], s[0:1], s[2:3]
	s_mov_b64 exec, s[2:3]
	s_cbranch_execz .LBB0_1664
	s_mov_b64 s[2:3], exec
	v_readlane_b32 s99, v253, 46
	s_cmp_lg_u32 s99, 0
	s_cbranch_scc1 .Lxnowb_4
	buffer_wbl2 sc1
.Lxnowb_4:
	s_waitcnt vmcnt(0)
	s_waitcnt vmcnt(0)
	v_mbcnt_lo_u32_b32 v0, s2, 0
	v_mbcnt_hi_u32_b32 v0, s3, v0
	v_cmp_eq_u32_e32 vcc, 0, v0
	s_and_saveexec_b64 s[6:7], vcc
	s_cbranch_execz .LBB0_1661
	s_bcnt1_i32_b64 s2, s[2:3]
	v_mov_b32_e32 v0, s2
	global_atomic_add v1, v0, s[14:15]

; DI void grid_bar(unsigned* ctr, unsigned target) {
;   asm volatile("s_waitcnt vmcnt(0)" ::: "memory");
;   __syncthreads();
;   if (threadIdx.x == 0) {
;     __builtin_amdgcn_fence(__ATOMIC_RELEASE, "agent");
;     asm volatile("s_waitcnt vmcnt(0)" ::: "memory");
;     (void)__hip_atomic_fetch_add(ctr, 1u, __ATOMIC_RELAXED, __HIP_MEMORY_SCOPE_AGENT);
;     while (__hip_atomic_load(ctr, __ATOMIC_RELAXED, __HIP_MEMORY_SCOPE_AGENT) < target) __builtin_amdgcn_s_sleep(1);
;     __builtin_amdgcn_fence(__ATOMIC_ACQUIRE, "agent");
.LBB0_1679:
	s_waitcnt vmcnt(0)
	s_add_i32 s75, s5, s33
	s_barrier
	s_mov_b64 s[0:1], exec
	v_readlane_b32 s2, v254, 13
	v_readlane_b32 s3, v254, 14
	s_and_b64 s[2:3], s[0:1], s[2:3]
	s_movk_i32 s60, 0x104
	s_mov_b64 exec, s[2:3]
	s_cbranch_execz .LBB0_1685
	s_mov_b64 s[2:3], exec
	v_readlane_b32 s99, v253, 46
	s_cmp_lg_u32 s99, 0
	s_cbranch_scc1 .Lxnowb_1
	buffer_wbl2 sc1
.Lxnowb_1:
	s_waitcnt vmcnt(0)
	s_waitcnt vmcnt(0)
	v_mbcnt_lo_u32_b32 v0, s2, 0
	v_mbcnt_hi_u32_b32 v0, s3, v0
	v_cmp_eq_u32_e32 vcc, 0, v0
	s_and_saveexec_b64 s[4:5], vcc
	s_cbranch_execz .LBB0_1682
	s_bcnt1_i32_b64 s2, s[2:3]
	v_mov_b32_e32 v0, s2
	v_readlane_b32 s2, v254, 52
	v_readlane_b32 s3, v254, 53
	s_nop 4
	global_atomic_add v1, v0, s[2:3]
